# even-layer prep phase: the 16 workgroups that also run fox_cumsum skip the K head-norm loop, the other 240 take all rows (critical-path rebalance)
# speedup vs baseline: 1.0057x; 1.0057x over previous
; #define TIDX launder((int)threadIdx.x)
; DI float bf2f(bf16_t v) { return __uint_as_float(((unsigned)v) << 16); }
; DI void headnorm_rows(bf16_t* buf, int rows, const float* __restrict__ gain, int item0, int nitems_total) {
;   const int lane = TIDX & 63, gw = blockIdx.x * 8 + (TIDX >> 6), nw = gridDim.x * 8;
;   const int sub = lane >> 4, l16 = lane & 15;
;   (void)item0; (void)nitems_total;
;   for (int it = gw; it < rows / 4; it += nw) {
;     bf16_t* rp = buf + (size_t)(it * 4 + sub) * 128 + l16 * 8;
;     bf16x8 raw = *(const bf16x8*)rp;
;     float f[8], s = 0.f;
; #pragma unroll
;     for (int e = 0; e < 8; ++e) { f[e] = bf2f((bf16_t)raw[e]); s += f[e] * f[e]; }
; DI void run_phase(const Params& p0, int ph) {
;     ...
;         headnorm_rows((bf16_t*)(ws + E_FK), 16 * T_, p.in[10] + e * 128, 0, 0);
.LBB0_361:
	s_and_b64 vcc, exec, s[0:1]
	s_cbranch_vccz .LBB0_371
	v_mov_b32_e32 v2, v199
	v_mov_b32_e32 v0, v199
	v_readlane_b32 s0, v250, 11
	v_ashrrev_i32_e32 v6, 6, v0
	s_nop 0
	s_sub_i32 s0, s0, 0x80
	v_add_u32_e32 v0, s0, v6
	s_movk_i32 s0, 0x4000
	v_cmp_gt_u32_e32 vcc, s0, v0
	s_and_saveexec_b64 s[0:1], vcc
	v_readlane_b32 s6, v252, 43
	v_readlane_b32 s7, v252, 44
	v_readlane_b32 s7, v252, 36
	s_mov_b32 s8, 0x800000
	s_movk_i32 s6, 0x780
	s_movk_i32 s7, 0x1e00
	s_cbranch_execz .LBB0_365
	v_readlane_b32 s2, v254, 20
	v_readlane_b32 s3, v254, 21
	s_lshl_b32 s2, s2, 7
	s_ashr_i32 s3, s2, 31
	v_readlane_b32 s12, v253, 14
	v_bfe_u32 v7, v2, 4, 2
	s_lshl_b64 s[2:3], s[2:3], 2
	v_readlane_b32 s16, v253, 18
	v_lshlrev_b32_e32 v2, 3, v2
	v_readlane_b32 s17, v253, 19
	s_add_u32 s2, s16, s2
	v_and_b32_e32 v4, 0x78, v2
	v_readlane_b32 s4, v253, 48
	s_addc_u32 s3, s17, s3
	v_lshlrev_b32_e32 v2, 1, v4
	s_waitcnt lgkmcnt(0)
	v_mov_b32_e32 v3, v1
	v_readlane_b32 s5, v253, 49
	v_lshlrev_b32_e32 v4, 2, v4
	v_mov_b32_e32 v5, v1
	v_lshl_add_u64 v[2:3], s[4:5], 0, v[2:3]
	s_mov_b64 s[4:5], 0x26145000
	v_lshl_add_u64 v[4:5], s[2:3], 0, v[4:5]
	v_lshlrev_b32_e32 v6, 2, v6
	v_readlane_b32 s2, v252, 35
	v_lshl_add_u64 v[2:3], v[2:3], 0, s[4:5]
	v_readlane_b32 s13, v253, 15
	s_sub_i32 s2, s2, 0x200
	v_add3_u32 v6, s2, v6, v7
	s_mov_b64 s[2:3], 0
	v_readlane_b32 s14, v253, 16
	v_readlane_b32 s15, v253, 17
	v_readlane_b32 s18, v253, 20
	v_readlane_b32 s19, v253, 21
	v_readlane_b32 s20, v253, 22
	v_readlane_b32 s21, v253, 23
	v_readlane_b32 s22, v253, 24
	v_readlane_b32 s23, v253, 25
	v_readlane_b32 s24, v253, 26
	v_readlane_b32 s25, v253, 27
	v_readlane_b32 s26, v253, 28
	v_readlane_b32 s27, v253, 29
	global_load_dwordx4 v[44:47], v[4:5], off offset:16
	global_load_dwordx4 v[48:51], v[4:5], off
	v_ashrrev_i32_e32 v7, 31, v6
	v_lshlrev_b64 v[8:9], 8, v[6:7]
	v_lshl_add_u64 v[18:19], v[2:3], 0, v[8:9]
	global_load_dwordx4 v[8:11], v[18:19], off
	s_waitcnt vmcnt(0)
